# MLA attention k-loop also rotated (immediate bf16 pack in softmax phase, prefetch of next MFMA phase first reads)
# baseline (speedup 1.0000x reference)
; #define LAS __attribute__((address_space(3)))
; #define GAS __attribute__((address_space(1)))
; #define ATT_LOADK(kt) do { const int k0_ = ATT_KEY0(kt); \
;         _Pragma("unroll") for (int p = 0; p < KPT; ++p) { const int c = tid + 512 * p; if (c < KCH) kr[p] = *(const GAS u32x4*)((const GAS char*)(Kb + (size_t)k0_ * DQK) + (unsigned)(c * 16)); } } while (0)
; #define ATT_LOADV(kt) do { const int k0_ = ATT_KEY0(kt); \
;         _Pragma("unroll") for (int p = 0; p < VPT; ++p) vr[p] = *(const GAS u32x4*)((const GAS char*)(Vb + k0_) + lvo[p]); } while (0)
; #define ATT_STOREK(buf) do { \
;         _Pragma("unroll") for (int p = 0; p < KPT; ++p) { const int c = tid + 512 * p; if (c < KCH) *(LAS u32x4*)(lds + (buf) * KBYTES + (c / CPR) * KS + (c % CPR) * 16) = kr[p]; } } while (0)
; template <int DQK, int DV, int NAT, int VSHIFT, int COMB> ...
;     ...
;         const int pos_q = qb * 256 + w * 32 + n;
;         const int qr = (qb - 1) * 4 + (w >> 1), qrs = min(max(qr - 4, 0), 120);
;         int lq_ = lane; asm volatile("" : "+v"(lq_));
;         const bf16_t* qp = Q + ((size_t)bv * TPB + qb * 256 + w * 32 + (lq_ & 31)) * DQK + (lq_ >> 5) * 8;
;         bf16x8 qg[DQK / 16];
; #pragma unroll
;         for (int ks = 0; ks < DQK / 16; ++ks) qg[ks] = *(const GAS bf16x8*)(qp + ks * 16);
;         LAS unsigned char* qs = lds + QOFF + w * QW + lane * 16;
;         f32x16 o[DV / 32];
; #pragma unroll
;         for (int dt = 0; dt < DV / 32; ++dt)
; #pragma unroll
;             for (int i = 0; i < 16; ++i) o[dt][i] = 0.f;
;         float l_run = 0.f;
;         f32x16 negm;
; #pragma unroll
;         for (int i = 0; i < 16; ++i) negm[i] = 0.f;
;     ...
;         __syncthreads();
;         if (NAT) { for (int i = tid; i < 465; i += 512) rpb_s[i] = rpb[vh * 465 + i]; }
; #pragma unroll
;         for (int ks = 0; ks < DQK / 16; ++ks) { if (!QREG) *(LAS bf16x8*)(qs + ks * 1024) = qg[ks]; }
;         if (K128) { ATT_DMAK(0, 0); ATT_DMAV(0, 0); ATT_DMAK(1, 1); ATT_DMAV(1, 1); ATT_DMAK(2, 2); asm volatile("s_waitcnt vmcnt(0)" ::: "memory"); }
;         else if (DMA) { ATT_DMAK(0, 0); ATT_DMAV(0, 0); ATT_DMAK(1, 1); asm volatile("s_waitcnt vmcnt(0)" ::: "memory"); }
;         else { ATT_LOADK(0); ATT_STOREK(0); ATT_LOADV(0); ATT_STOREV(0); ATT_LOADK(1); ATT_STOREK(1); }
;         __syncthreads();
;         f32x16 sA0, sA1, sB0, sB1;
;         ATT_QK(sA0, sA1, 0);
;         __syncthreads();
.LBB0_501:
	s_lshl_b32 s0, s28, 8
	s_and_b32 s0, s0, 0x1f00
	s_cmpk_gt_i32 s28, 0x7ff
	s_cselect_b32 s34, 4, 0x84
	s_addk_i32 s0, 0x100
	s_cmpk_gt_i32 s28, 0x7ff
	s_cselect_b32 s29, 0, s0
	s_ashr_i32 s0, s28, 5
	s_add_i32 s1, s28, 0xfffff800
	s_cmpk_gt_i32 s28, 0x7ff
	s_cselect_b32 s37, s1, s0
	s_and_b32 s30, s37, 15
	s_ashr_i32 s31, s37, 4
	s_mul_i32 s0, s30, 0x420000
	v_readlane_b32 s11, v253, 53
	s_add_u32 s0, s11, s0
	v_readlane_b32 s11, v253, 54
	s_mul_i32 s10, s31, 0x4200
	s_addc_u32 s11, s11, 0
	s_mul_hi_i32 s1, s31, 0x4200
	s_add_u32 s0, s0, s10
	s_mul_i32 s5, s37, 0x2100
	s_addc_u32 s1, s11, s1
	s_mul_hi_i32 s4, s37, 0x2100
	v_lshl_add_u64 v[2:3], s[0:1], 0, v[164:165]
	v_mov_b32_e32 v0, v173
	s_add_u32 s0, s29, s5
	v_mov_b32_e32 v7, s25
	v_and_or_b32 v6, v0, 31, s24
	s_addc_u32 s1, 0, s4
	v_lshl_add_u64 v[6:7], s[0:1], 0, v[6:7]
	v_readlane_b32 s0, v253, 40
	v_readlane_b32 s1, v253, 41
	s_movk_i32 s4, 0xc0
	s_mul_i32 s9, s37, 0x18c000
	v_mov_b64_e32 v[8:9], s[0:1]
	v_mad_u64_u32 v[8:9], s[0:1], v6, s4, v[8:9]
	v_readlane_b32 s0, v253, 42
	s_mul_hi_i32 s8, s37, 0x18c000
	v_ashrrev_i32_e32 v0, 2, v0
	v_readlane_b32 s1, v253, 43
	s_add_u32 s0, s0, s9
	v_and_b32_e32 v6, -8, v0
	s_addc_u32 s1, s1, s8
	v_mad_i32_i24 v9, v7, s4, v9
	v_ashrrev_i32_e32 v7, 31, v6
	s_add_u32 s4, s0, 0x6000
	v_lshl_add_u64 v[6:7], v[6:7], 1, v[8:9]
	s_addc_u32 s5, s1, 0
	s_mov_b32 m0, s26
	global_load_dwordx4 v[114:117], v[6:7], off
	global_load_dwordx4 v[118:121], v[6:7], off offset:32
	global_load_dwordx4 v[122:125], v[6:7], off offset:64
	global_load_dwordx4 v[126:129], v[6:7], off offset:96
	global_load_dwordx4 v[130:133], v[6:7], off offset:128
	global_load_dwordx4 v[134:137], v[6:7], off offset:160
	s_add_u32 s8, s0, 0x3000
	v_lshl_add_u64 v[6:7], s[0:1], 0, v[160:161]
	s_addc_u32 s9, s1, 0
	s_waitcnt vmcnt(0)
	s_barrier
	global_load_lds_dwordx4 v[6:7], off
	v_lshl_add_u64 v[6:7], s[0:1], 0, v[162:163]
	s_add_i32 m0, s26, 0x2000
	v_lshl_add_u64 v[4:5], v[2:3], 0, s[74:75]
	global_load_lds_dwordx4 v[6:7], off
	s_add_i32 m0, s26, 0x10000
	v_add_u32_e32 v0, v159, v184
	global_load_lds_dwordx4 v[2:3], off
	v_lshl_add_u64 v[2:3], s[8:9], 0, v[160:161]
	s_add_i32 m0, s26, 0x4000
	s_mov_b32 s36, 2
	global_load_lds_dwordx4 v[2:3], off
	v_lshl_add_u64 v[2:3], s[8:9], 0, v[162:163]
	s_add_i32 m0, s26, 0x6000
	s_mov_b32 s8, 0
	global_load_lds_dwordx4 v[2:3], off
	s_add_i32 m0, s26, 0x12000
	v_lshl_add_u64 v[2:3], s[4:5], 0, v[160:161]
	global_load_lds_dwordx4 v[4:5], off
	s_add_i32 m0, s26, 0x8000
	s_movk_i32 s35, 0x4000
	global_load_lds_dwordx4 v[2:3], off
	v_lshl_add_u64 v[2:3], s[4:5], 0, v[162:163]
	s_add_i32 m0, s26, 0xa000
	s_nop 0
	global_load_lds_dwordx4 v[2:3], off
	s_waitcnt vmcnt(0)
	s_waitcnt vmcnt(0) lgkmcnt(0)
	s_barrier
	ds_read_b128 v[2:5], v0
	ds_read_b128 v[6:9], v0 offset:8192
	v_add_u32_e32 v0, v159, v185
	ds_read_b128 v[10:13], v0
	ds_read_b128 v[14:17], v0 offset:8192
	v_add_u32_e32 v0, v159, v186
	ds_read_b128 v[18:21], v0
	ds_read_b128 v[22:25], v0 offset:8192
	v_add_u32_e32 v0, v159, v187
	ds_read_b128 v[26:29], v0
	ds_read_b128 v[30:33], v0 offset:8192
	v_add_u32_e32 v0, v159, v188
	ds_read_b128 v[34:37], v0
	ds_read_b128 v[38:41], v0 offset:8192
	v_add_u32_e32 v0, v159, v189
	ds_read_b128 v[42:45], v0
	ds_read_b128 v[82:85], v0 offset:8192
	s_waitcnt lgkmcnt(11)
	v_mfma_f32_32x32x16_bf16 v[66:81], v[2:5], v[114:117], 0
	s_mov_b32 s22, s8
	s_mov_b32 s23, s8
	s_mov_b32 s9, s8
	s_mov_b32 s10, s8
	s_mov_b32 s11, s8
	s_mov_b32 s12, s8
	s_mov_b32 s13, s8
	s_waitcnt lgkmcnt(10)
	v_mfma_f32_32x32x16_bf16 v[50:65], v[6:9], v[114:117], 0
	s_mov_b32 s14, s8
	s_mov_b32 s15, s8
	s_mov_b32 s16, s8
	s_mov_b32 s17, s8
	s_mov_b32 s18, s8
	s_mov_b32 s19, s8
	s_mov_b32 s20, s8
	s_waitcnt lgkmcnt(9)
	v_mfma_f32_32x32x16_bf16 v[66:81], v[10:13], v[118:121], v[66:81]
	s_mov_b32 s21, s8
	s_waitcnt lgkmcnt(8)
	v_mfma_f32_32x32x16_bf16 v[50:65], v[14:17], v[118:121], v[50:65]
	s_waitcnt lgkmcnt(7)
	v_mfma_f32_32x32x16_bf16 v[66:81], v[18:21], v[122:125], v[66:81]
	s_waitcnt lgkmcnt(6)
	v_mfma_f32_32x32x16_bf16 v[50:65], v[22:25], v[122:125], v[50:65]
	s_waitcnt lgkmcnt(5)
	v_mfma_f32_32x32x16_bf16 v[66:81], v[26:29], v[126:129], v[66:81]
	s_waitcnt lgkmcnt(4)
	v_mfma_f32_32x32x16_bf16 v[50:65], v[30:33], v[126:129], v[50:65]
	s_waitcnt lgkmcnt(3)
	v_mfma_f32_32x32x16_bf16 v[66:81], v[34:37], v[130:133], v[66:81]
	s_waitcnt lgkmcnt(2)
	v_mfma_f32_32x32x16_bf16 v[50:65], v[38:41], v[130:133], v[50:65]
	s_waitcnt lgkmcnt(1)
	v_mfma_f32_32x32x16_bf16 v[66:81], v[42:45], v[134:137], v[66:81]
	v_mov_b64_e32 v[48:49], s[22:23]
	v_mov_b64_e32 v[46:47], s[20:21]
	v_mov_b64_e32 v[44:45], s[18:19]
	v_mov_b64_e32 v[42:43], s[16:17]
	v_mov_b64_e32 v[40:41], s[14:15]
	v_mov_b64_e32 v[38:39], s[12:13]
	v_mov_b64_e32 v[36:37], s[10:11]
	s_waitcnt lgkmcnt(0)
	v_mfma_f32_32x32x16_bf16 v[50:65], v[82:85], v[134:137], v[50:65]
	v_mov_b64_e32 v[34:35], s[8:9]
	s_mov_b64 s[18:19], 0xb50c000
	s_mov_b64 s[16:17], 0xb509000
	s_mov_b64 s[14:15], 0x6000
	v_mov_b32_e32 v0, 0x420000
	v_mad_u64_u32 v[2:3], s[0:1], s30, v0, v[166:167]
	v_mad_i64_i32 v[176:177], s[0:1], s31, v203, v[2:3]
	v_mov_b32_e32 v2, v1
	v_mov_b32_e32 v3, v1
	v_mov_b32_e32 v4, v1
	v_mov_b32_e32 v5, v1
	v_mov_b32_e32 v6, v1
	v_mov_b32_e32 v7, v1
	v_mov_b32_e32 v8, v1
	v_mov_b32_e32 v9, v1
	v_mov_b32_e32 v10, v1
	v_mov_b32_e32 v11, v1
	v_mov_b32_e32 v12, v1
	v_mov_b32_e32 v13, v1
	v_mov_b32_e32 v14, v1
	v_mov_b32_e32 v15, v1
	v_mov_b32_e32 v16, v1
	v_mov_b32_e32 v17, v1
	v_mov_b32_e32 v18, v1
	v_mov_b32_e32 v19, v1
	v_mov_b32_e32 v20, v1
	v_mov_b32_e32 v21, v1
	v_mov_b32_e32 v22, v1
	v_mov_b32_e32 v23, v1
	v_mov_b32_e32 v24, v1
	v_mov_b32_e32 v25, v1
	v_mov_b32_e32 v26, v1
	v_mov_b32_e32 v27, v1
	v_mov_b32_e32 v28, v1
	v_mov_b32_e32 v29, v1
	v_mov_b32_e32 v30, v1
	v_mov_b32_e32 v31, v1
	v_mov_b32_e32 v0, v1
	v_mov_b64_e32 v[32:33], v[30:31]
	v_mad_i64_i32 v[178:179], s[0:1], s37, v204, v[168:169]
	v_mad_i64_i32 v[180:181], s[0:1], s37, v204, v[174:175]
	v_mov_b32_e32 v183, 0
	v_mov_b64_e32 v[30:31], v[28:29]
	v_mov_b64_e32 v[28:29], v[26:27]
	v_mov_b64_e32 v[26:27], v[24:25]
	v_mov_b64_e32 v[24:25], v[22:23]
	v_mov_b64_e32 v[22:23], v[20:21]
	v_mov_b64_e32 v[20:21], v[18:19]
	v_mov_b64_e32 v[18:19], v[16:17]
	v_mov_b64_e32 v[16:17], v[14:15]
	v_mov_b64_e32 v[14:15], v[12:13]
	v_mov_b64_e32 v[12:13], v[10:11]
	v_mov_b64_e32 v[10:11], v[8:9]
	v_mov_b64_e32 v[8:9], v[6:7]
	v_mov_b64_e32 v[6:7], v[4:5]
	v_mov_b64_e32 v[4:5], v[2:3]
	v_mov_b64_e32 v[2:3], v[0:1]
	s_barrier
	v_readlane_b32 s0, v252, 7
	s_cmpk_lt_u32 s0, 0x100
	s_cbranch_scc0 .Lmpre_skip
	s_mov_b64 s[4:5], -1
	s_mov_b64 s[10:11], 0
.Lmv_pre_top:
	v_exp_f32_e32 v138, v66
	v_exp_f32_e32 v139, v67
	v_exp_f32_e32 v140, v50
	v_exp_f32_e32 v141, v51
	v_add_f32_e32 v155, 0, v138
	v_add_f32_e32 v146, 0, v139
	v_cvt_pk_bf16_f32 v82, v138, v139
	v_exp_f32_e32 v142, v68
	v_exp_f32_e32 v143, v69
	v_add_f32_e32 v156, 0, v140
	v_add_f32_e32 v147, 0, v141
	v_cvt_pk_bf16_f32 v90, v140, v141
	v_exp_f32_e32 v144, v52
	v_exp_f32_e32 v145, v53
	v_add_f32_e32 v155, v142, v155
	v_add_f32_e32 v146, v143, v146
	v_cvt_pk_bf16_f32 v83, v142, v143
	v_exp_f32_e32 v138, v70
	v_exp_f32_e32 v139, v71
	v_add_f32_e32 v156, v144, v156
	v_add_f32_e32 v147, v145, v147
	v_cvt_pk_bf16_f32 v91, v144, v145
	v_exp_f32_e32 v140, v54
	v_exp_f32_e32 v141, v55
	v_add_f32_e32 v155, v138, v155
	v_add_f32_e32 v146, v139, v146
	v_cvt_pk_bf16_f32 v84, v138, v139
	v_exp_f32_e32 v142, v72
	v_exp_f32_e32 v143, v73
	v_add_f32_e32 v156, v140, v156
	v_add_f32_e32 v147, v141, v147
	v_cvt_pk_bf16_f32 v92, v140, v141
	v_exp_f32_e32 v144, v56
	v_exp_f32_e32 v145, v57
	v_add_f32_e32 v155, v142, v155
	v_add_f32_e32 v146, v143, v146
	v_cvt_pk_bf16_f32 v85, v142, v143
	v_exp_f32_e32 v138, v74
	v_exp_f32_e32 v139, v75
	v_add_f32_e32 v156, v144, v156
	v_add_f32_e32 v147, v145, v147
	v_cvt_pk_bf16_f32 v93, v144, v145
	v_exp_f32_e32 v140, v58
	v_exp_f32_e32 v141, v59
	v_add_f32_e32 v155, v138, v155
	v_add_f32_e32 v146, v139, v146
	v_cvt_pk_bf16_f32 v86, v138, v139
	v_exp_f32_e32 v142, v76
	v_exp_f32_e32 v143, v77
	v_add_f32_e32 v156, v140, v156
	v_add_f32_e32 v147, v141, v147
	v_cvt_pk_bf16_f32 v94, v140, v141
	v_exp_f32_e32 v144, v60
	v_exp_f32_e32 v145, v61
	v_add_f32_e32 v155, v142, v155
	v_add_f32_e32 v146, v143, v146
	v_cvt_pk_bf16_f32 v87, v142, v143
	v_exp_f32_e32 v138, v78
	v_exp_f32_e32 v139, v79
	v_add_f32_e32 v156, v144, v156
	v_add_f32_e32 v147, v145, v147
	v_cvt_pk_bf16_f32 v95, v144, v145
	v_exp_f32_e32 v140, v62
	v_exp_f32_e32 v141, v63
	v_add_f32_e32 v155, v138, v155
	v_add_f32_e32 v146, v139, v146
	v_cvt_pk_bf16_f32 v88, v138, v139
	v_exp_f32_e32 v142, v80
	v_exp_f32_e32 v143, v81
	v_add_f32_e32 v156, v140, v156
	v_add_f32_e32 v147, v141, v147
	v_cvt_pk_bf16_f32 v96, v140, v141
	v_exp_f32_e32 v144, v64
	v_exp_f32_e32 v145, v65
	v_add_f32_e32 v155, v142, v155
	v_add_f32_e32 v146, v143, v146
	v_cvt_pk_bf16_f32 v89, v142, v143
	s_nop 0
	v_add_f32_e32 v156, v144, v156
	v_add_f32_e32 v147, v145, v147
	v_cvt_pk_bf16_f32 v97, v144, v145
	v_add_f32_e32 v155, v155, v146
	v_add_f32_e32 v156, v156, v147
	v_add_f32_e32 v157, v155, v156
	s_nop 0
	v_cmp_ngt_f32_e32 vcc, s72, v157
	s_nop 1
	s_or_b64 vcc, vcc, s[4:5]
	s_andn2_b64 vcc, vcc, s[10:11]
	s_cbranch_vccz .Lmv_pre_fast
	v_max3_f32 v154, v66, v67, v68
	v_max3_f32 v154, v154, v69, v70
	v_max3_f32 v154, v154, v71, v72
	v_max3_f32 v154, v154, v73, v74
	v_max3_f32 v154, v154, v75, v76
	v_max3_f32 v154, v154, v77, v78
	v_max3_f32 v154, v154, v79, v80
	v_max3_f32 v154, v154, v81, v50
	v_max3_f32 v154, v154, v51, v52
	v_max3_f32 v154, v154, v53, v54
	v_max3_f32 v154, v154, v55, v56
	v_max3_f32 v154, v154, v57, v58
	v_max3_f32 v154, v154, v59, v60
	v_max3_f32 v154, v154, v61, v62
	v_max3_f32 v154, v154, v63, v64
	v_max_f32_e32 v154, v154, v65
	ds_bpermute_b32 v148, v195, v154
	s_waitcnt lgkmcnt(0)
	v_max_f32_e32 v154, v154, v148
	s_and_b64 vcc, exec, s[4:5]
	s_cbranch_vccnz .Lmv_pre_anchor
	v_max_f32_e32 v154, 0, v154
	v_exp_f32_e64 v149, -v154
	s_nop 7
	s_nop 7
	v_mul_f32_e32 v183, v183, v149
	v_mul_f32_e32 v2, v2, v149
	v_mul_f32_e32 v3, v3, v149
	v_mul_f32_e32 v4, v4, v149
	v_mul_f32_e32 v5, v5, v149
	v_mul_f32_e32 v6, v6, v149
	v_mul_f32_e32 v7, v7, v149
	v_mul_f32_e32 v8, v8, v149
	v_mul_f32_e32 v9, v9, v149
	v_mul_f32_e32 v10, v10, v149
	v_mul_f32_e32 v11, v11, v149
	v_mul_f32_e32 v12, v12, v149
	v_mul_f32_e32 v13, v13, v149
	v_mul_f32_e32 v14, v14, v149
	v_mul_f32_e32 v15, v15, v149
	v_mul_f32_e32 v16, v16, v149
	v_mul_f32_e32 v17, v17, v149
	v_mul_f32_e32 v18, v18, v149
	v_mul_f32_e32 v19, v19, v149
	v_mul_f32_e32 v20, v20, v149
	v_mul_f32_e32 v21, v21, v149
	v_mul_f32_e32 v22, v22, v149
	v_mul_f32_e32 v23, v23, v149
	v_mul_f32_e32 v24, v24, v149
	v_mul_f32_e32 v25, v25, v149
	v_mul_f32_e32 v26, v26, v149
	v_mul_f32_e32 v27, v27, v149
	v_mul_f32_e32 v28, v28, v149
	v_mul_f32_e32 v29, v29, v149
	v_mul_f32_e32 v30, v30, v149
	v_mul_f32_e32 v31, v31, v149
	v_mul_f32_e32 v32, v32, v149
	v_mul_f32_e32 v33, v33, v149
.Lmv_pre_anchor:
	v_sub_f32_e32 v66, v66, v154
	v_sub_f32_e32 v67, v67, v154
	v_sub_f32_e32 v68, v68, v154
	v_sub_f32_e32 v69, v69, v154
	v_sub_f32_e32 v70, v70, v154
	v_sub_f32_e32 v71, v71, v154
	v_sub_f32_e32 v72, v72, v154
	v_sub_f32_e32 v73, v73, v154
	v_sub_f32_e32 v74, v74, v154
	v_sub_f32_e32 v75, v75, v154
	v_sub_f32_e32 v76, v76, v154
	v_sub_f32_e32 v77, v77, v154
	v_sub_f32_e32 v78, v78, v154
	v_sub_f32_e32 v79, v79, v154
	v_sub_f32_e32 v80, v80, v154
	v_sub_f32_e32 v81, v81, v154
	v_sub_f32_e32 v50, v50, v154
	v_sub_f32_e32 v51, v51, v154
	v_sub_f32_e32 v52, v52, v154
	v_sub_f32_e32 v53, v53, v154
	v_sub_f32_e32 v54, v54, v154
	v_sub_f32_e32 v55, v55, v154
	v_sub_f32_e32 v56, v56, v154
	v_sub_f32_e32 v57, v57, v154
	v_sub_f32_e32 v58, v58, v154
	v_sub_f32_e32 v59, v59, v154
	v_sub_f32_e32 v60, v60, v154
	v_sub_f32_e32 v61, v61, v154
	v_sub_f32_e32 v62, v62, v154
	v_sub_f32_e32 v63, v63, v154
	v_sub_f32_e32 v64, v64, v154
	v_sub_f32_e32 v65, v65, v154
	v_sub_f32_e32 v34, v34, v154
	v_sub_f32_e32 v35, v35, v154
	v_sub_f32_e32 v36, v36, v154
	v_sub_f32_e32 v37, v37, v154
	v_sub_f32_e32 v38, v38, v154
	v_sub_f32_e32 v39, v39, v154
	v_sub_f32_e32 v40, v40, v154
	v_sub_f32_e32 v41, v41, v154
	v_sub_f32_e32 v42, v42, v154
	v_sub_f32_e32 v43, v43, v154
	v_sub_f32_e32 v44, v44, v154
	v_sub_f32_e32 v45, v45, v154
	v_sub_f32_e32 v46, v46, v154
	v_sub_f32_e32 v47, v47, v154
	v_sub_f32_e32 v48, v48, v154
	v_sub_f32_e32 v49, v49, v154
	s_mov_b64 s[10:11], -1
	s_branch .Lmv_pre_top
.Lmv_pre_fast:
	v_add_f32_e32 v183, v183, v157
.Lmpre_skip:
.LBB0_502:
	s_add_i32 s9, s36, 2
	s_add_i32 s13, s36, -1
	s_and_b32 s12, s13, 3
	s_add_i32 s0, s36, 1
	s_cmp_ge_u32 s0, s34
	s_cbranch_scc1 .Lmk_skip1
	s_add_i32 s0, s8, 0xc000
	s_and_b32 s0, s0, 0xc000
	s_add_i32 s0, s26, s0
	v_lshl_add_u64 v[198:199], s[84:85], 0, v[180:181]
	s_mov_b32 m0, s0
	v_lshl_add_u64 v[198:199], v[198:199], 0, s[16:17]
	global_load_lds_dwordx4 v[198:199], off
	v_lshl_add_u64 v[198:199], s[84:85], 0, v[178:179]
	s_add_i32 m0, s0, 0x2000
	v_lshl_add_u64 v[198:199], v[198:199], 0, s[16:17]
	global_load_lds_dwordx4 v[198:199], off
.Lmk_skip1:
	s_cmp_ge_u32 s9, s34
	s_cbranch_scc1 .Lmk_skip2
	s_and_b32 s0, s8, 0x8000
	s_add_i32 s0, s26, s0
	v_lshl_add_u64 v[198:199], s[84:85], 0, v[180:181]
	s_mov_b32 m0, s0
	v_lshl_add_u64 v[198:199], v[198:199], 0, s[18:19]
	global_load_lds_dwordx4 v[198:199], off
	v_lshl_add_u64 v[198:199], s[84:85], 0, v[178:179]
	s_add_i32 m0, s0, 0x2000
	v_lshl_add_u64 v[198:199], v[198:199], 0, s[18:19]
	global_load_lds_dwordx4 v[198:199], off
.Lmk_skip2:
	v_lshl_add_u32 v0, s12, 14, v159
	s_add_i32 s0, s35, 0xffffc000
	s_and_b32 s0, s0, 0x4000
	v_add_u32_e32 v154, s0, v190
	v_add_u32_e32 v210, v0, v184
	v_add_u32_e32 v211, v0, v185
	v_add_u32_e32 v212, v0, v186
	v_add_u32_e32 v213, v0, v187
	v_add_u32_e32 v214, v0, v188
	v_add_u32_e32 v215, v0, v189
	v_add_u32_e32 v216, v154, v191
	v_add_u32_e32 v217, v154, v192
	v_add_u32_e32 v196, v154, v193
	v_add_u32_e32 v197, v154, v194
	ds_read_b128 v[98:101], v210
	ds_read_b128 v[102:105], v210 offset:8192
	ds_read_b128 v[106:109], v211
	ds_read_b128 v[110:113], v211 offset:8192
	v_readlane_b32 s0, v252, 7
	s_cmpk_lt_u32 s0, 0x100
	s_cbranch_scc1 .Lmtop_skip
	s_cmp_eq_u32 s36, 2
	s_cselect_b64 s[4:5], -1, 0
	s_mov_b64 s[10:11], 0

.Lmtop_skip:
	s_setprio 1
	s_waitcnt lgkmcnt(3)
	v_mfma_f32_32x32x16_bf16 v[66:81], v[98:101], v[114:117], v[34:49]
	ds_read_b128 v[98:101], v212
	s_waitcnt lgkmcnt(3)
	v_mfma_f32_32x32x16_bf16 v[50:65], v[102:105], v[114:117], v[34:49]
	ds_read_b128 v[102:105], v212 offset:8192
	s_waitcnt lgkmcnt(3)
	v_mfma_f32_32x32x16_bf16 v[66:81], v[106:109], v[118:121], v[66:81]
	ds_read_b128 v[106:109], v213
	s_waitcnt lgkmcnt(3)
	v_mfma_f32_32x32x16_bf16 v[50:65], v[110:113], v[118:121], v[50:65]
	ds_read_b128 v[110:113], v213 offset:8192
	s_waitcnt lgkmcnt(3)
	v_mfma_f32_32x32x16_bf16 v[66:81], v[98:101], v[122:125], v[66:81]
	ds_read_b128 v[98:101], v214
	s_waitcnt lgkmcnt(3)
	v_mfma_f32_32x32x16_bf16 v[50:65], v[102:105], v[122:125], v[50:65]
	ds_read_b128 v[102:105], v214 offset:8192
	s_waitcnt lgkmcnt(3)
	v_mfma_f32_32x32x16_bf16 v[66:81], v[106:109], v[126:129], v[66:81]
	ds_read_b128 v[106:109], v215
	s_waitcnt lgkmcnt(3)
	v_mfma_f32_32x32x16_bf16 v[50:65], v[110:113], v[126:129], v[50:65]
	ds_read_b128 v[110:113], v215 offset:8192
	s_waitcnt lgkmcnt(3)
	v_mfma_f32_32x32x16_bf16 v[66:81], v[98:101], v[130:133], v[66:81]
	ds_read_b128 v[98:101], v216
	s_waitcnt lgkmcnt(3)
	v_mfma_f32_32x32x16_bf16 v[50:65], v[102:105], v[130:133], v[50:65]
	ds_read_b128 v[102:105], v216 offset:4096
	s_waitcnt lgkmcnt(3)
	v_mfma_f32_32x32x16_bf16 v[66:81], v[106:109], v[134:137], v[66:81]
	ds_read_b128 v[106:109], v217
	s_waitcnt lgkmcnt(3)
	v_mfma_f32_32x32x16_bf16 v[50:65], v[110:113], v[134:137], v[50:65]
	ds_read_b128 v[110:113], v217 offset:4096
	s_waitcnt lgkmcnt(3)
	v_mfma_f32_32x32x16_bf16 v[2:17], v[98:101], v[82:85], v[2:17]
	ds_read_b128 v[98:101], v196
	s_waitcnt lgkmcnt(3)
	v_mfma_f32_32x32x16_bf16 v[18:33], v[102:105], v[82:85], v[18:33]
	ds_read_b128 v[102:105], v196 offset:4096
	s_waitcnt lgkmcnt(3)
	v_mfma_f32_32x32x16_bf16 v[2:17], v[106:109], v[86:89], v[2:17]
	ds_read_b128 v[106:109], v197
	s_waitcnt lgkmcnt(3)
	v_mfma_f32_32x32x16_bf16 v[18:33], v[110:113], v[86:89], v[18:33]
	ds_read_b128 v[110:113], v197 offset:4096
	s_waitcnt lgkmcnt(3)
	v_mfma_f32_32x32x16_bf16 v[2:17], v[98:101], v[90:93], v[2:17]
	s_waitcnt lgkmcnt(2)
	v_mfma_f32_32x32x16_bf16 v[18:33], v[102:105], v[90:93], v[18:33]
	s_waitcnt lgkmcnt(1)
	v_mfma_f32_32x32x16_bf16 v[2:17], v[106:109], v[94:97], v[2:17]
	s_waitcnt lgkmcnt(0)
	v_mfma_f32_32x32x16_bf16 v[18:33], v[110:113], v[94:97], v[18:33]
	s_setprio 0
	s_add_i32 s8, s8, 0x8000
	s_and_b32 s0, s8, 0x8000
	v_add_u32_e32 v0, s0, v159
	v_lshl_add_u32 v154, s12, 13, v190
	v_add_u32_e32 v210, v0, v184
	v_add_u32_e32 v211, v0, v185
	v_add_u32_e32 v212, v0, v186
	v_add_u32_e32 v213, v0, v187
	v_add_u32_e32 v214, v0, v188
	v_add_u32_e32 v215, v0, v189
	v_add_u32_e32 v216, v154, v191
	v_add_u32_e32 v217, v154, v192
	v_add_u32_e32 v196, v154, v193
	v_add_u32_e32 v197, v154, v194
	ds_read_b128 v[98:101], v210
	ds_read_b128 v[102:105], v210 offset:8192
	ds_read_b128 v[106:109], v211
	ds_read_b128 v[110:113], v211 offset:8192
	s_mov_b64 s[4:5], 0
	s_mov_b64 s[10:11], 0

.Lmv_mid_fast:
	v_add_f32_e32 v183, v183, v157
	s_cmp_ge_u32 s36, s34
	s_cbranch_scc1 .Lmv_skip1
	s_and_b32 s0, s35, 0x4000
	s_add_i32 m0, s27, s0
	v_lshl_add_u64 v[198:199], s[84:85], 0, v[176:177]
	v_lshl_add_u64 v[198:199], v[198:199], 0, s[78:79]
	global_load_lds_dwordx4 v[198:199], off
.Lmv_skip1:
	s_add_i32 s0, s36, 1
	s_cmp_ge_u32 s0, s34
	s_cbranch_scc1 .Lmv_skip2
	s_add_i32 s0, s35, 0x2000
	s_and_b32 s0, s0, 0x6000
	s_add_i32 m0, s27, s0
	v_lshl_add_u64 v[198:199], s[84:85], 0, v[176:177]
	v_lshl_add_u64 v[198:199], v[198:199], 0, s[80:81]
	global_load_lds_dwordx4 v[198:199], off
.Lmv_skip2:
	s_setprio 1
	s_waitcnt lgkmcnt(3)
	v_mfma_f32_32x32x16_bf16 v[66:81], v[98:101], v[114:117], v[34:49]
	ds_read_b128 v[98:101], v212
	s_waitcnt lgkmcnt(3)
	v_mfma_f32_32x32x16_bf16 v[50:65], v[102:105], v[114:117], v[34:49]
	ds_read_b128 v[102:105], v212 offset:8192
	s_waitcnt lgkmcnt(3)
	v_mfma_f32_32x32x16_bf16 v[66:81], v[106:109], v[118:121], v[66:81]
	ds_read_b128 v[106:109], v213
	s_waitcnt lgkmcnt(3)
	v_mfma_f32_32x32x16_bf16 v[50:65], v[110:113], v[118:121], v[50:65]
	ds_read_b128 v[110:113], v213 offset:8192
	s_waitcnt lgkmcnt(3)
	v_mfma_f32_32x32x16_bf16 v[66:81], v[98:101], v[122:125], v[66:81]
	ds_read_b128 v[98:101], v214
	s_waitcnt lgkmcnt(3)
	v_mfma_f32_32x32x16_bf16 v[50:65], v[102:105], v[122:125], v[50:65]
	ds_read_b128 v[102:105], v214 offset:8192
	s_waitcnt lgkmcnt(3)
	v_mfma_f32_32x32x16_bf16 v[66:81], v[106:109], v[126:129], v[66:81]
	ds_read_b128 v[106:109], v215
	s_waitcnt lgkmcnt(3)
	v_mfma_f32_32x32x16_bf16 v[50:65], v[110:113], v[126:129], v[50:65]
	ds_read_b128 v[110:113], v215 offset:8192
	s_waitcnt lgkmcnt(3)
	v_mfma_f32_32x32x16_bf16 v[66:81], v[98:101], v[130:133], v[66:81]
	ds_read_b128 v[98:101], v216
	s_waitcnt lgkmcnt(3)
	v_mfma_f32_32x32x16_bf16 v[50:65], v[102:105], v[130:133], v[50:65]
	ds_read_b128 v[102:105], v216 offset:4096
	s_waitcnt lgkmcnt(3)
	v_mfma_f32_32x32x16_bf16 v[66:81], v[106:109], v[134:137], v[66:81]
	ds_read_b128 v[106:109], v217
	s_waitcnt lgkmcnt(3)
	v_mfma_f32_32x32x16_bf16 v[50:65], v[110:113], v[134:137], v[50:65]
	ds_read_b128 v[110:113], v217 offset:4096
	s_waitcnt lgkmcnt(3)
	v_mfma_f32_32x32x16_bf16 v[2:17], v[98:101], v[82:85], v[2:17]
	ds_read_b128 v[98:101], v196
	s_waitcnt lgkmcnt(3)
	v_mfma_f32_32x32x16_bf16 v[18:33], v[102:105], v[82:85], v[18:33]
	ds_read_b128 v[102:105], v196 offset:4096
	s_waitcnt lgkmcnt(3)
	v_mfma_f32_32x32x16_bf16 v[2:17], v[106:109], v[86:89], v[2:17]
	ds_read_b128 v[106:109], v197
	s_waitcnt lgkmcnt(3)
	v_mfma_f32_32x32x16_bf16 v[18:33], v[110:113], v[86:89], v[18:33]
	ds_read_b128 v[110:113], v197 offset:4096
	s_waitcnt lgkmcnt(3)
	v_mfma_f32_32x32x16_bf16 v[2:17], v[98:101], v[90:93], v[2:17]
	s_waitcnt lgkmcnt(2)
	v_mfma_f32_32x32x16_bf16 v[18:33], v[102:105], v[90:93], v[18:33]
	s_waitcnt lgkmcnt(1)
	v_mfma_f32_32x32x16_bf16 v[2:17], v[106:109], v[94:97], v[2:17]
	s_waitcnt lgkmcnt(0)
	v_mfma_f32_32x32x16_bf16 v[18:33], v[110:113], v[94:97], v[18:33]
	s_setprio 0
	s_cmp_ge_u32 s36, s34
	s_cbranch_scc1 .Lmend_skip
	v_readlane_b32 s0, v252, 7
	s_cmpk_lt_u32 s0, 0x100
	s_cbranch_scc0 .Lmend_skip
	s_mov_b64 s[4:5], 0
	s_mov_b64 s[10:11], 0

; #define LAS __attribute__((address_space(3)))
; #define ATT_LOADK(kt) do { const int k0_ = ATT_KEY0(kt); \
;         _Pragma("unroll") for (int p = 0; p < KPT; ++p) { const int c = tid + 512 * p; if (c < KCH) kr[p] = *(const GAS u32x4*)((const GAS char*)(Kb + (size_t)k0_ * DQK) + (unsigned)(c * 16)); } } while (0)
; #define ATT_LOADV(kt) do { const int k0_ = ATT_KEY0(kt); \
;         _Pragma("unroll") for (int p = 0; p < VPT; ++p) vr[p] = *(const GAS u32x4*)((const GAS char*)(Vb + k0_) + lvo[p]); } while (0)
; #define ATT_STOREK(buf) do { \
;         _Pragma("unroll") for (int p = 0; p < KPT; ++p) { const int c = tid + 512 * p; if (c < KCH) *(LAS u32x4*)(lds + (buf) * KBYTES + (c / CPR) * KS + (c % CPR) * 16) = kr[p]; } } while (0)
; #define ATT_STOREV(buf) do { \
;         _Pragma("unroll") for (int p = 0; p < VPT; ++p) { const int c = tid + 512 * p; *(LAS u32x4*)(lds + VOFF + (buf) * VBYTES + (c >> 3) * VS + (c & 7) * 16) = vr[p]; } } while (0)
; #define ATT_DMAK(kt, slot) do { const int k0_ = ATT_KEY0(kt); \
;         _Pragma("unroll") for (int i_ = 0; i_ < DKPT; ++i_) \
;             __builtin_amdgcn_global_load_lds((const unsigned*)((const char*)(Kb + (size_t)k0_ * DQK) + dko[i_]), (LAS unsigned*)(lds + (slot) * KBYTES + i_ * 8192 + w * 1024), 16, 0, 0); } while (0)
; template <int DQK, int DV, int NAT, int VSHIFT, int COMB> ...
;     ...
;         __syncthreads();
;         if (NAT) { for (int i = tid; i < 465; i += 512) rpb_s[i] = rpb[vh * 465 + i]; }
; #pragma unroll
;         for (int ks = 0; ks < DQK / 16; ++ks) { if (!QREG) *(LAS bf16x8*)(qs + ks * 1024) = qg[ks]; }
;         if (K128) { ATT_DMAK(0, 0); ATT_DMAV(0, 0); ATT_DMAK(1, 1); ATT_DMAV(1, 1); ATT_DMAK(2, 2); asm volatile("s_waitcnt vmcnt(0)" ::: "memory"); }
;         else if (DMA) { ATT_DMAK(0, 0); ATT_DMAV(0, 0); ATT_DMAK(1, 1); asm volatile("s_waitcnt vmcnt(0)" ::: "memory"); }
;         else { ATT_LOADK(0); ATT_STOREK(0); ATT_LOADV(0); ATT_STOREV(0); ATT_LOADK(1); ATT_STOREK(1); }
;         __syncthreads();
;         f32x16 sA0, sA1, sB0, sB1;
;         ATT_QK(sA0, sA1, 0);
;         __syncthreads();
;         for (int kt = 0; kt < nkt; kt += 2) {
;             ATT_STEP(sA0, sA1, sB0, sB1, kt, 0);
;             if (kt + 1 < nkt) ATT_STEP(sB0, sB1, sA0, sA1, kt + 1, 1);
;         }
.Lmend_skip:
	s_waitcnt vmcnt(0)
	s_barrier
.LBB0_525:
	s_addk_i32 s35, 0x4000
	v_lshl_add_u64 v[176:177], v[176:177], 0, s[76:77]
	v_lshl_add_u64 v[178:179], v[178:179], 0, s[14:15]
	s_cmp_ge_u32 s36, s34
	v_lshl_add_u64 v[180:181], v[180:181], 0, s[14:15]
	s_cbranch_scc1 .LBB0_500
	s_mov_b32 s36, s9
	s_branch .LBB0_502
